# grid barrier between the two merge GEMMs dropped (their only cross-phase dependence is same-thread M)
# baseline (speedup 1.0000x reference)
.LBB0_406:
	s_cmp_gt_i32 s93, 5
	s_cselect_b64 s[4:5], -1, 0
	s_cmp_lg_u32 s94, 0
	s_cselect_b64 s[8:9], -1, 0
	s_and_b64 s[4:5], s[4:5], s[8:9]
	s_andn2_b64 vcc, exec, s[4:5]
	s_waitcnt vmcnt(0)
	s_branch .LBB0_456
	s_waitcnt vmcnt(0)
	s_waitcnt vmcnt(0) lgkmcnt(0)
	s_barrier
	s_and_saveexec_b64 s[4:5], s[90:91]
	s_cbranch_execz .LBB0_455
	s_add_i32 s1, 0, 0x20080
	v_mov_b32_e32 v0, s1
	s_waitcnt vmcnt(0) expcnt(0) lgkmcnt(0)
	ds_read_b32 v2, v0
	s_add_i32 s1, 0, 0x20084
	v_mov_b32_e32 v0, s1
	ds_read_b32 v0, v0
	s_waitcnt lgkmcnt(1)
	v_cmp_ne_u32_e32 vcc, 0, v2
	s_cbranch_vccnz .LBB0_423
	s_load_dwordx2 s[10:11], s[6:7], 0x4
	s_add_u32 s6, s86, 0x1000
	s_addc_u32 s7, s87, 0
	s_add_u32 s8, s86, 0x1100
	s_addc_u32 s9, s87, 0
	s_waitcnt lgkmcnt(0)
	s_mul_i32 s0, s10, s0
	s_add_u32 s10, s86, 0x1200
	s_mul_i32 s0, s0, s11
	s_addc_u32 s11, s87, 0
	s_add_u32 s12, s86, 0x1300
	s_addc_u32 s13, s87, 0
	s_mov_b32 s1, 1
	v_mov_b32_e32 v16, 0
	s_branch .LBB0_411

.LBB0_1472:
	s_cmp_gt_i32 s93, 18
	s_cselect_b64 s[4:5], -1, 0
	s_cmp_lg_u32 s94, 0
	s_cselect_b64 s[8:9], -1, 0
	s_and_b64 s[4:5], s[4:5], s[8:9]
	s_andn2_b64 vcc, exec, s[4:5]
	s_waitcnt vmcnt(0)
	s_branch .LBB0_1522
	s_waitcnt vmcnt(0)
	s_waitcnt vmcnt(0) lgkmcnt(0)
	s_barrier
	s_and_saveexec_b64 s[4:5], s[90:91]
	s_cbranch_execz .LBB0_1521
	s_add_i32 s1, 0, 0x20080
	v_mov_b32_e32 v0, s1
	s_waitcnt vmcnt(0) expcnt(0) lgkmcnt(0)
	ds_read_b32 v2, v0
	s_add_i32 s1, 0, 0x20084
	v_mov_b32_e32 v0, s1
	ds_read_b32 v0, v0
	s_waitcnt lgkmcnt(1)
	v_cmp_ne_u32_e32 vcc, 0, v2
	s_cbranch_vccnz .LBB0_1489
	s_load_dwordx2 s[10:11], s[6:7], 0x4
	s_add_u32 s6, s86, 0x1000
	s_addc_u32 s7, s87, 0
	s_add_u32 s8, s86, 0x1100
	s_addc_u32 s9, s87, 0
	s_waitcnt lgkmcnt(0)
	s_mul_i32 s0, s10, s0
	s_add_u32 s10, s86, 0x1200
	s_mul_i32 s0, s0, s11
	s_addc_u32 s11, s87, 0
	s_add_u32 s12, s86, 0x1300
	s_addc_u32 s13, s87, 0
	s_mov_b32 s1, 1
	v_mov_b32_e32 v16, 0
	s_branch .LBB0_1477
